# XCC-local rounds without a release step: the waiters watch the XCC arrival counter reach (round+1)*workgroups; the leader does its own acquire at once (rounds that order against the neighbour batch ke
# baseline (speedup 1.0000x reference)
; __device__ __forceinline__ unsigned xb_add(unsigned* p, unsigned v) { return __hip_atomic_fetch_add(p, v, __ATOMIC_RELAXED, __HIP_MEMORY_SCOPE_AGENT); }
; __device__ __forceinline__ void xcd_barrier(const XcdBarrier& b, const int tid) {
;     ...
;         const unsigned old = xb_add(&bar[XB_XSUB(b.x)], 1u);
;         const unsigned gen = old / nloc;
;         if (old + 1u == (gen + 1u) * nloc) {
.Lxb_nf3:
	s_movk_i32 s4, 0xf78
	s_lshr_b32 s4, s4, s48
	v_readlane_b32 s5, v255, 21
	s_and_b32 s4, s4, 1
	s_and_b32 s99, s4, s5
	s_cmp_eq_u32 s99, 0
	s_cbranch_scc1 .Lxb_md
	s_cmp_eq_u32 s48, 5
	s_cbranch_scc1 .Lxb_md
	s_cmp_eq_u32 s48, 10
	s_cbranch_scc1 .Lxb_md
	s_mov_b32 s99, 2

; __device__ __forceinline__ unsigned xb_ld(unsigned* p)              { return __hip_atomic_load(p, __ATOMIC_RELAXED, __HIP_MEMORY_SCOPE_AGENT); }
; __device__ __forceinline__ unsigned xb_add(unsigned* p, unsigned v) { return __hip_atomic_fetch_add(p, v, __ATOMIC_RELAXED, __HIP_MEMORY_SCOPE_AGENT); }
; #define XB_SPIN(cond, bar) do { unsigned _sp = 0; while (cond) { __builtin_amdgcn_s_sleep(1); \
;     if ((++_sp & 255u) == 0u) { if (xb_ld(&(bar)[XB_TMO])) break; if (_sp > XB_SPIN_CAP) { atomicAdd(&(bar)[XB_TMO], 1u); break; } } } } while (0)
; __device__ __forceinline__ void xcd_barrier(const XcdBarrier& b, const int tid) {
;     ...
;         const unsigned old = xb_add(&bar[XB_XSUB(b.x)], 1u);
;         const unsigned gen = old / nloc;
;         if (old + 1u == (gen + 1u) * nloc) {
;     ...
;         } else {
;             XB_SPIN(xb_ld(&bar[XB_XGEN(b.x)]) == gen, bar);
;             __builtin_amdgcn_fence(__ATOMIC_ACQUIRE, "agent");
;             asm volatile("s_waitcnt vmcnt(0)" ::: "memory");
;         }
.LBB0_588:
	s_or_b64 exec, exec, s[2:3]
	v_cvt_f32_u32_e32 v5, v3
	s_waitcnt vmcnt(0)
	v_readfirstlane_b32 s2, v4
	v_sub_u32_e32 v4, 0, v3
	v_rcp_iflag_f32_e32 v5, v5
	v_add_u32_e32 v6, s2, v0
	v_mul_f32_e32 v5, 0x4f7ffffe, v5
	v_cvt_u32_f32_e32 v5, v5
	v_mul_lo_u32 v0, v4, v5
	v_mul_hi_u32 v0, v5, v0
	v_add_u32_e32 v0, v5, v0
	v_mul_hi_u32 v0, v6, v0
	v_mul_lo_u32 v4, v0, v3
	v_sub_u32_e32 v4, v6, v4
	v_add_u32_e32 v5, 1, v0
	v_cmp_ge_u32_e32 vcc, v4, v3
	s_nop 1
	v_cndmask_b32_e32 v0, v0, v5, vcc
	v_sub_u32_e32 v5, v4, v3
	v_cndmask_b32_e32 v4, v4, v5, vcc
	v_add_u32_e32 v5, 1, v0
	v_cmp_ge_u32_e32 vcc, v4, v3
	v_add_u32_e32 v4, 1, v6
	s_nop 0
	v_cndmask_b32_e32 v0, v0, v5, vcc
	v_mul_lo_u32 v5, v3, v0
	v_add_u32_e32 v3, v5, v3
	v_cmp_ne_u32_e32 vcc, v4, v3
	v_readfirstlane_b32 s98, v0
	s_and_saveexec_b64 s[2:3], vcc
	s_xor_b64 s[2:3], exec, s[2:3]
	s_cbranch_execz .LBB0_602
	v_readlane_b32 s4, v250, 11
	v_readlane_b32 s5, v250, 12
	v_add_u32_e32 v0, 1, v0
	s_cmp_eq_u32 s99, 2
	s_cbranch_scc0 .Lxb_pg
	v_readlane_b32 s4, v250, 9
	v_readlane_b32 s5, v250, 10
	v_mov_b32_e32 v0, v3
.Lxb_pg:
	s_waitcnt lgkmcnt(0)
	s_nop 4
	s_mov_b32 s100, s4
	s_mov_b32 s101, s5
	global_load_dword v2, v1, s[4:5] sc1
	s_waitcnt vmcnt(0)
	v_cmp_lt_u32_e32 vcc, v2, v0
	s_and_saveexec_b64 s[4:5], vcc
	s_cbranch_execz .LBB0_601
	s_mov_b32 s20, 1
	s_mov_b64 s[6:7], 0
	s_branch .LBB0_592

; __device__ __forceinline__ unsigned xb_ld(unsigned* p)              { return __hip_atomic_load(p, __ATOMIC_RELAXED, __HIP_MEMORY_SCOPE_AGENT); }
; #define XB_SPIN(cond, bar) do { unsigned _sp = 0; while (cond) { __builtin_amdgcn_s_sleep(1); \
;     if ((++_sp & 255u) == 0u) { if (xb_ld(&(bar)[XB_TMO])) break; if (_sp > XB_SPIN_CAP) { atomicAdd(&(bar)[XB_TMO], 1u); break; } } } } while (0)
; __device__ __forceinline__ void xcd_barrier(const XcdBarrier& b, const int tid) {
;     ...
;         } else {
;             XB_SPIN(xb_ld(&bar[XB_XGEN(b.x)]) == gen, bar);
;             __builtin_amdgcn_fence(__ATOMIC_ACQUIRE, "agent");
;             asm volatile("s_waitcnt vmcnt(0)" ::: "memory");
;         }
.LBB0_596:
	s_mov_b32 s10, s100
	s_mov_b32 s11, s101
	s_add_i32 s20, s20, 1
	s_mov_b64 s[30:31], -1
	s_nop 2
	global_load_dword v2, v1, s[10:11] sc1
	s_waitcnt vmcnt(0)
	v_cmp_ge_u32_e32 vcc, v2, v0
	s_orn2_b64 s[10:11], vcc, exec
	s_branch .LBB0_591

; __device__ __forceinline__ unsigned xb_add(unsigned* p, unsigned v) { return __hip_atomic_fetch_add(p, v, __ATOMIC_RELAXED, __HIP_MEMORY_SCOPE_AGENT); }
; __device__ __forceinline__ void xcd_barrier(const XcdBarrier& b, const int tid) {
;     ...
;         const unsigned old = xb_add(&bar[XB_XSUB(b.x)], 1u);
;         const unsigned gen = old / nloc;
;         if (old + 1u == (gen + 1u) * nloc) {
.LBB0_602:
	s_andn2_saveexec_b64 s[2:3], s[2:3]
	s_cbranch_execz .LBB0_622
	s_mov_b64 s[2:3], exec
	s_cmp_eq_u32 s99, 0
	s_cbranch_scc1 .Lxb_glob
	s_cmp_eq_u32 s48, 4
	s_cbranch_scc1 .Lxb_pub
	s_cmp_eq_u32 s48, 9
	s_cbranch_scc1 .Lxb_pub
	s_cmp_eq_u32 s48, 5
	s_cbranch_scc1 .Lxb_wt
	s_cmp_eq_u32 s48, 10
	s_cbranch_scc1 .Lxb_wt
	s_branch .Lxb_rel

; __device__ __forceinline__ unsigned xb_ld(unsigned* p)              { return __hip_atomic_load(p, __ATOMIC_RELAXED, __HIP_MEMORY_SCOPE_AGENT); }
; __device__ __forceinline__ unsigned xb_add(unsigned* p, unsigned v) { return __hip_atomic_fetch_add(p, v, __ATOMIC_RELAXED, __HIP_MEMORY_SCOPE_AGENT); }
; #define XB_SPIN(cond, bar) do { unsigned _sp = 0; while (cond) { __builtin_amdgcn_s_sleep(1); \
;     if ((++_sp & 255u) == 0u) { if (xb_ld(&(bar)[XB_TMO])) break; if (_sp > XB_SPIN_CAP) { atomicAdd(&(bar)[XB_TMO], 1u); break; } } } } while (0)
; __device__ __forceinline__ void xcd_barrier(const XcdBarrier& b, const int tid) {
;     ...
;             __builtin_amdgcn_fence(__ATOMIC_RELEASE, "agent");
;             asm volatile("s_waitcnt vmcnt(0)" ::: "memory");
;             const unsigned og = xb_add(&bar[XB_TOP], 1u);
;             const unsigned tg = og / nx;
;             if (og + 1u == (tg + 1u) * nx) xb_add(&bar[XB_TOPGEN], 1u);
;             else XB_SPIN(xb_ld(&bar[XB_TOPGEN]) == tg, bar);
;             __builtin_amdgcn_fence(__ATOMIC_ACQUIRE, "agent");
;             xb_add(&bar[XB_XGEN(b.x)], 1u);
;             asm volatile("s_waitcnt vmcnt(0)" ::: "memory");
.Lxb_rel:
	v_readlane_b32 s4, v250, 11
	v_readlane_b32 s5, v250, 12
	v_mov_b32_e32 v4, 1
	s_nop 4
	global_atomic_add v1, v4, s[4:5]
	buffer_inv sc1
	s_waitcnt vmcnt(0)
	s_branch .LBB0_622

; __global__ void __launch_bounds__(512, 2) fwd_kernel(Args a) {
;     extern __shared__ __attribute__((aligned(16))) unsigned char lds_raw[];
	.amdhsa_kernel _Z10fwd_kernel4Args
		.amdhsa_group_segment_fixed_size 0
		.amdhsa_private_segment_fixed_size 0
		.amdhsa_kernarg_size 416
		.amdhsa_user_sgpr_count 2
		.amdhsa_user_sgpr_dispatch_ptr 0
		.amdhsa_user_sgpr_queue_ptr 0
		.amdhsa_user_sgpr_kernarg_segment_ptr 1
		.amdhsa_user_sgpr_dispatch_id 0
		.amdhsa_user_sgpr_kernarg_preload_length 0
		.amdhsa_user_sgpr_kernarg_preload_offset 0
		.amdhsa_user_sgpr_private_segment_size 0
		.amdhsa_uses_dynamic_stack 0
		.amdhsa_enable_private_segment 0
		.amdhsa_system_sgpr_workgroup_id_x 1
		.amdhsa_system_sgpr_workgroup_id_y 0
		.amdhsa_system_sgpr_workgroup_id_z 0
		.amdhsa_system_sgpr_workgroup_info 0
		.amdhsa_system_vgpr_workitem_id 2
		.amdhsa_next_free_vgpr 256
		.amdhsa_next_free_sgpr 102
		.amdhsa_accum_offset 256
		.amdhsa_reserve_vcc 1
		.amdhsa_float_round_mode_32 0
		.amdhsa_float_round_mode_16_64 0
		.amdhsa_float_denorm_mode_32 3
		.amdhsa_float_denorm_mode_16_64 3
		.amdhsa_dx10_clamp 1
		.amdhsa_ieee_mode 1
		.amdhsa_fp16_overflow 0
		.amdhsa_tg_split 0
		.amdhsa_exception_fp_ieee_invalid_op 0
		.amdhsa_exception_fp_denorm_src 0
		.amdhsa_exception_fp_ieee_div_zero 0
		.amdhsa_exception_fp_ieee_overflow 0
		.amdhsa_exception_fp_ieee_underflow 0
		.amdhsa_exception_fp_ieee_inexact 0
		.amdhsa_exception_int_div_zero 0
	.end_amdhsa_kernel

; __global__ void __launch_bounds__(512, 2) fwd_kernel(Args a) {
;     extern __shared__ __attribute__((aligned(16))) unsigned char lds_raw[];
.Lfunc_end0:
	.size	_Z10fwd_kernel4Args, .Lfunc_end0-_Z10fwd_kernel4Args
	.set _Z10fwd_kernel4Args.num_vgpr, 256
	.set _Z10fwd_kernel4Args.num_agpr, 0
	.set _Z10fwd_kernel4Args.numbered_sgpr, 102
	.set _Z10fwd_kernel4Args.num_named_barrier, 0
	.set _Z10fwd_kernel4Args.private_seg_size, 0
	.set _Z10fwd_kernel4Args.uses_vcc, 1
	.set _Z10fwd_kernel4Args.uses_flat_scratch, 0
	.set _Z10fwd_kernel4Args.has_dyn_sized_stack, 0
	.set _Z10fwd_kernel4Args.has_recursion, 0
	.set _Z10fwd_kernel4Args.has_indirect_call, 0

; __global__ void __launch_bounds__(512, 2) fwd_kernel(Args a) {
;     extern __shared__ __attribute__((aligned(16))) unsigned char lds_raw[];
amdhsa.kernels:
  - .agpr_count:     0
    .args:
      - .offset:         0
        .size:           160
        .value_kind:     by_value
      - .offset:         160
        .size:           4
        .value_kind:     hidden_block_count_x
      - .offset:         164
        .size:           4
        .value_kind:     hidden_block_count_y
      - .offset:         168
        .size:           4
        .value_kind:     hidden_block_count_z
      - .offset:         172
        .size:           2
        .value_kind:     hidden_group_size_x
      - .offset:         174
        .size:           2
        .value_kind:     hidden_group_size_y
      - .offset:         176
        .size:           2
        .value_kind:     hidden_group_size_z
      - .offset:         178
        .size:           2
        .value_kind:     hidden_remainder_x
      - .offset:         180
        .size:           2
        .value_kind:     hidden_remainder_y
      - .offset:         182
        .size:           2
        .value_kind:     hidden_remainder_z
      - .offset:         200
        .size:           8
        .value_kind:     hidden_global_offset_x
      - .offset:         208
        .size:           8
        .value_kind:     hidden_global_offset_y
      - .offset:         216
        .size:           8
        .value_kind:     hidden_global_offset_z
      - .offset:         224
        .size:           2
        .value_kind:     hidden_grid_dims
      - .offset:         248
        .size:           8
        .value_kind:     hidden_multigrid_sync_arg
      - .offset:         280
        .size:           4
        .value_kind:     hidden_dynamic_lds_size
    .group_segment_fixed_size: 0
    .kernarg_segment_align: 8
    .kernarg_segment_size: 416
    .language:       OpenCL C
    .language_version:
      - 2
      - 0
    .max_flat_workgroup_size: 512
    .name:           _Z10fwd_kernel4Args
    .private_segment_fixed_size: 0
    .sgpr_count:     108
    .sgpr_spill_count: 407
    .symbol:         _Z10fwd_kernel4Args.kd
    .uniform_work_group_size: 1
    .uses_dynamic_stack: false
    .vgpr_count:     256
    .vgpr_spill_count: 0
    .wavefront_size: 64
